# phase 2: filter units dealt against the input GEMM's tile tail (workgroups with a 15th tile take 12 units, the rest 18/17)
# speedup vs baseline: 1.0069x; 1.0015x over previous
; __device__ __forceinline__ void ph_filter(const Params& P, char* smem) {
;     ...
;   constexpr int NTT = (SEQ + CTX_LEN) / 64, NCT = HY_CH / 64;
;   const float max_decay = logf(1e-2f) / 0.3f, min_decay = logf(1e-2f) / 1.5f;
;   for (int u = blockIdx.x; u < NTT * NCT; u += gridDim.x) {
;     const int tt = u % NTT, ct = u / NTT;
;     const int gp0 = tt * 64, c0 = ct * 64;
;     const bool isc = gp0 >= SEQ;
;     const int L = isc ? CTX_LEN : SEQ;
;     const int t0 = isc ? gp0 - SEQ : gp0;
;     __syncthreads();
.LBB0_389:
	s_cmpk_lt_i32 s2, 0x1040
	s_cselect_b64 s[0:1], -1, 0
	s_mov_b64 s[4:5], s[96:97]
	v_writelane_b32 v254, s0, 8
	s_cmpk_gt_i32 s2, 0x103f
	s_nop 0
	v_writelane_b32 v254, s1, 9
	s_cbranch_scc1 .LBB0_435
	s_load_dwordx2 s[10:11], s[4:5], 0x178
	s_load_dwordx4 s[12:15], s[4:5], 0x88
	s_movk_i32 s0, 0x104
	s_movk_i32 s1, 0x1000
	s_movk_i32 s33, 0x1ff
	s_waitcnt lgkmcnt(0)
	s_add_u32 s16, s10, 0x327cc000
	s_addc_u32 s17, s11, 0
	s_movk_i32 s40, 0xdff
	s_movk_i32 s41, 0x2000
	s_add_i32 s42, 0, 0x4100
	s_movk_i32 s43, 0x1dff
	s_movk_i32 s44, 0x3fff
	s_mov_b32 s45, 0x447fc000
	s_mov_b32 s46, 0x3fb8aa3b
	s_mov_b32 s47, 0xc2ce8ed0
	s_mov_b32 s48, 0x42b17218
	s_mov_b32 s49, 0x3abdc000
	v_mov_b32_e32 v1, 1
	v_mov_b32_e32 v26, -2
	v_mov_b32_e32 v27, 10
	v_mov_b32_e32 v28, 0x7f800000
	s_mov_b32 s50, s2
	s_mov_b32 s51, s84
	s_movk_i32 s52, 0x1040
	s_cmp_lg_u32 s84, 0x100
	s_cbranch_scc1 .Lflt_go
	s_and_b32 s53, s2, 7
	s_lshr_b32 s54, s2, 3
	s_mov_b32 s51, 1
	s_cmp_eq_u32 s53, 0
	s_cbranch_scc1 .Lflt_l0
	s_cmp_eq_u32 s53, 1
	s_cbranch_scc0 .Lflt_e0
	s_cmp_lt_u32 s54, 24
	s_cbranch_scc0 .Lflt_e1
	s_add_u32 s54, s54, 32
.Lflt_l0:
	s_mul_i32 s50, s54, 12
	s_add_u32 s52, s50, 12
	s_branch .Lflt_go
.Lflt_e1:
	s_add_u32 s54, s54, 0xa8
	s_branch .Lflt_e
.Lflt_e0:
	s_mul_i32 s54, s54, 6
	s_add_u32 s54, s54, s53
	s_sub_u32 s54, s54, 2
.Lflt_e:
	s_cmp_lt_u32 s54, 0x58
	s_cbranch_scc0 .Lflt_e17
	s_mul_i32 s50, s54, 18
	s_add_u32 s50, s50, 0x2a0
	s_add_u32 s52, s50, 18
	s_branch .Lflt_go
.Lflt_e17:
	s_sub_u32 s54, s54, 0x58
	s_mul_i32 s50, s54, 17
	s_add_u32 s50, s50, 0x8d0
	s_add_u32 s52, s50, 17

; __device__ __forceinline__ void ph_filter(const Params& P, char* smem) {
;     ...
;     const float tn = (float)(t0 + t) / (float)(L - 1);
; #pragma unroll
;     for (int q = 0; q < 16; ++q) {
;       const int col = cg * 16 + q, cc = col / 2, dir = col % 2, c = c0 + cc;
;       const float delta = fabsf(min_decay + (max_decay - min_decay) * (float)c / (float)(HY_CH - 1));
;       const float v = (acc[q] + P.f_b4[dir * HY_CH + c]) * expf(-tn * delta);
;       if (isc) filtc[((size_t)c * 2 + dir) * CTX_LEN + t0 + t] = v;
;       else filt[((size_t)c * 2 + dir) * SEQ + t0 + t] = v;
;     }
.LBB0_391:
	v_cvt_f32_i32_e32 v7, v8
	s_waitcnt vmcnt(0)
	v_add_f32_e32 v4, v5, v4
	v_mul_f32_e32 v7, 0xc1447cbd, v7
	v_div_scale_f32 v9, s[4:5], s45, s45, v7
	v_rcp_f32_e32 v10, v9
	v_div_scale_f32 v11, vcc, v7, s45, v7
	s_add_u32 s4, s10, s26
	v_fma_f32 v12, -v9, v10, 1.0
	v_fmac_f32_e32 v10, v12, v10
	v_mul_f32_e32 v12, v11, v10
	v_fma_f32 v13, -v9, v12, v11
	v_fmac_f32_e32 v12, v13, v10
	v_fma_f32 v9, -v9, v12, v11
	v_div_fmas_f32 v9, v9, v10, v12
	v_div_fixup_f32 v7, v9, s45, v7
	v_add_f32_e32 v7, 0xc0447cbd, v7
	v_mul_f32_e64 v7, v29, |v7|
	v_mul_f32_e32 v9, 0x3fb8aa3b, v7
	v_fma_f32 v10, v7, s46, -v9
	v_rndne_f32_e32 v11, v9
	v_fmac_f32_e32 v10, 0x32a5705f, v7
	v_sub_f32_e32 v9, v9, v11
	v_add_f32_e32 v9, v9, v10
	v_cvt_i32_f32_e32 v10, v11
	v_exp_f32_e32 v9, v9
	v_cmp_ngt_f32_e32 vcc, s47, v7
	s_addc_u32 s5, s11, s27
	s_add_i32 s50, s50, s51
	v_ldexp_f32 v5, v9, v10
	v_cndmask_b32_e32 v5, 0, v5, vcc
	v_cmp_nlt_f32_e32 vcc, s48, v7
	v_ashrrev_i32_e32 v9, 31, v8
	v_ashrrev_i32_e32 v7, 31, v6
	v_cndmask_b32_e32 v5, v28, v5, vcc
	v_mul_f32_e32 v10, v5, v4
	v_lshlrev_b64 v[4:5], s24, v[8:9]
	v_lshl_add_u64 v[4:5], s[4:5], 0, v[4:5]
	v_lshlrev_b64 v[6:7], s8, v[6:7]
	v_lshl_add_u64 v[4:5], v[4:5], 0, v[6:7]
	v_lshl_add_u64 v[4:5], s[18:19], 2, v[4:5]
	v_lshl_add_u64 v[2:3], v[2:3], 2, v[4:5]
	s_cmp_lt_i32 s50, s52
	global_store_dword v[2:3], v10, off
	s_cbranch_scc0 .LBB0_435
